# Y5: out-proj GEMM early-buffer-release schedule (on EP2 stack)
# speedup vs baseline: 1.0815x; 1.0076x over previous
.LBB0_1002:
	s_mov_b64 s[10:11], -1
	s_and_b64 vcc, exec, s[8:9]
	s_cbranch_vccz .LBB0_994
	s_ashr_i32 s7, s6, 31
	s_lshl_b64 s[8:9], s[6:7], 18
	s_add_u32 s16, s82, s8
	s_addc_u32 s17, s83, s9
	s_ashr_i32 s5, s4, 31
	s_lshl_b64 s[10:11], s[4:5], 18
	v_mov_b32_e32 v38, v156
	s_add_u32 s22, s12, s10
	s_addc_u32 s23, s13, s11
	v_readfirstlane_b32 s24, v38
	s_ashr_i32 s5, s24, 6
	v_bfe_u32 v0, v38, 3, 3
	v_lshl_or_b32 v2, s5, 5, v0
	v_min_i32_e32 v4, 0x7f, v2
	v_or_b32_e32 v10, 8, v2
	v_ashrrev_i32_e32 v5, 31, v4
	v_lshrrev_b32_e32 v11, 1, v10
	v_lshlrev_b64 v[4:5], 11, v[4:5]
	v_lshlrev_b32_e32 v0, 4, v38
	s_waitcnt vmcnt(0)
	v_and_b32_e32 v40, 48, v38
	v_ashrrev_i32_e32 v3, 31, v2
	v_xor_b32_e32 v11, v11, v38
	v_min_i32_e32 v12, 0x7f, v10
	v_or_b32_e32 v20, 16, v2
	v_or_b32_e32 v28, 24, v2
	v_lshl_add_u64 v[4:5], s[16:17], 0, v[4:5]
	v_and_b32_e32 v41, 0x70, v0
	v_bitop3_b32 v0, v0, v40, s19 bitop3:0x6c
	v_lshlrev_b64 v[6:7], 11, v[2:3]
	v_ashrrev_i32_e32 v13, 31, v12
	v_lshlrev_b32_e32 v11, 4, v11
	v_min_i32_e32 v22, 0x7f, v20
	v_min_i32_e32 v30, 0x7f, v28
	s_lshl_b32 s5, s5, 12
	v_lshl_add_u64 v[4:5], v[4:5], 0, v[0:1]
	v_lshl_add_u64 v[8:9], s[22:23], 0, v[6:7]
	v_lshlrev_b64 v[12:13], 11, v[12:13]
	v_and_b32_e32 v14, 0x70, v11
	v_ashrrev_i32_e32 v11, 31, v10
	v_ashrrev_i32_e32 v23, 31, v22
	v_ashrrev_i32_e32 v31, 31, v30
	s_add_i32 s15, s5, 0x4000
	s_mov_b32 m0, s5
	v_lshl_add_u64 v[8:9], v[8:9], 0, v[0:1]
	v_lshl_add_u64 v[12:13], s[16:17], 0, v[12:13]
	v_mov_b32_e32 v15, v1
	v_lshlrev_b64 v[16:17], 11, v[10:11]
	v_lshlrev_b64 v[22:23], 11, v[22:23]
	v_lshrrev_b32_e32 v29, 1, v28
	v_lshlrev_b64 v[30:31], 11, v[30:31]
	s_barrier
	global_load_lds_dwordx4 v[4:5], off
	s_mov_b32 m0, s15
	v_lshl_add_u64 v[12:13], v[12:13], 0, v[14:15]
	v_lshl_add_u64 v[18:19], s[22:23], 0, v[16:17]
	v_lshl_add_u64 v[22:23], s[16:17], 0, v[22:23]
	v_ashrrev_i32_e32 v21, 31, v20
	v_xor_b32_e32 v29, v29, v38
	v_lshl_add_u64 v[30:31], s[16:17], 0, v[30:31]
	global_load_lds_dwordx4 v[8:9], off
	s_or_b32 m0, s5, 0x400
	s_add_i32 s16, s5, 0x4400
	v_lshl_add_u64 v[18:19], v[18:19], 0, v[14:15]
	v_lshlrev_b64 v[24:25], 11, v[20:21]
	v_lshlrev_b32_e32 v29, 4, v29
	global_load_lds_dwordx4 v[12:13], off
	s_mov_b32 m0, s16
	v_lshl_add_u64 v[22:23], v[22:23], 0, v[0:1]
	v_lshl_add_u64 v[26:27], s[22:23], 0, v[24:25]
	v_and_b32_e32 v32, 0x70, v29
	v_ashrrev_i32_e32 v29, 31, v28
	global_load_lds_dwordx4 v[18:19], off
	s_or_b32 m0, s5, 0x800
	s_add_i32 s17, s5, 0x4800
	v_lshl_add_u64 v[26:27], v[26:27], 0, v[0:1]
	v_mov_b32_e32 v33, v1
	v_lshlrev_b64 v[34:35], 11, v[28:29]
	global_load_lds_dwordx4 v[22:23], off
	s_mov_b32 m0, s17
	v_lshl_add_u64 v[30:31], v[30:31], 0, v[32:33]
	v_lshl_add_u64 v[36:37], s[22:23], 0, v[34:35]
	global_load_lds_dwordx4 v[26:27], off
	s_or_b32 m0, s5, 0xc00
	s_add_i32 s22, s5, 0x4c00
	v_lshl_add_u64 v[36:37], v[36:37], 0, v[32:33]
	global_load_lds_dwordx4 v[30:31], off
	s_mov_b32 m0, s22
	s_lshr_b32 s23, s24, 1
	global_load_lds_dwordx4 v[36:37], off
	s_and_b32 s23, s23, 0x1ffffc0
	v_cmp_gt_i64_e32 vcc, s[30:31], v[2:3]
	s_add_u32 s10, s0, s10
	s_addc_u32 s11, s1, s11
	v_cndmask_b32_e32 v3, 0, v3, vcc
	v_cndmask_b32_e32 v2, v164, v2, vcc
	v_lshlrev_b64 v[2:3], 11, v[2:3]
	v_lshl_add_u64 v[104:105], s[8:9], 0, v[2:3]
	v_lshl_add_u64 v[2:3], s[10:11], 0, v[6:7]
	v_cmp_gt_i64_e32 vcc, s[30:31], v[10:11]
	v_lshl_add_u64 v[106:107], v[2:3], 0, v[0:1]
	v_and_b32_e32 v39, 31, v38
	v_cndmask_b32_e32 v3, 0, v11, vcc
	v_cndmask_b32_e32 v2, v164, v10, vcc
	v_lshlrev_b64 v[2:3], 11, v[2:3]
	v_lshl_add_u64 v[108:109], s[8:9], 0, v[2:3]
	v_lshl_add_u64 v[2:3], s[10:11], 0, v[16:17]
	v_cmp_gt_i64_e32 vcc, s[30:31], v[20:21]
	v_bfe_u32 v4, v38, 5, 1
	v_lshrrev_b32_e32 v5, 1, v38
	v_lshl_add_u64 v[110:111], v[2:3], 0, v[14:15]
	v_cndmask_b32_e32 v3, 0, v21, vcc
	v_cndmask_b32_e32 v2, v164, v20, vcc
	v_or_b32_e32 v9, s23, v39
	v_and_or_b32 v12, s24, 64, v39
	v_bitop3_b32 v5, v4, v5, 7 bitop3:0x78
	v_lshlrev_b64 v[2:3], 11, v[2:3]
	v_bfe_u32 v8, v38, 1, 3
	v_lshlrev_b32_e32 v9, 7, v9
	v_lshl_or_b32 v12, v12, 7, v163
	v_lshlrev_b32_e32 v5, 4, v5
	v_lshl_add_u64 v[112:113], s[8:9], 0, v[2:3]
	v_lshl_add_u64 v[2:3], s[10:11], 0, v[24:25]
	v_cmp_gt_i64_e32 vcc, s[30:31], v[28:29]
	v_or_b32_e32 v71, v9, v5
	v_or_b32_e32 v73, v12, v5
	v_bitop3_b32 v5, v4, v8, 2 bitop3:0x36
	v_lshl_add_u64 v[114:115], v[2:3], 0, v[0:1]
	v_cndmask_b32_e32 v3, 0, v29, vcc
	v_cndmask_b32_e32 v2, v164, v28, vcc
	v_lshlrev_b32_e32 v5, 4, v5
	v_lshlrev_b64 v[2:3], 11, v[2:3]
	s_waitcnt vmcnt(0)
	v_or_b32_e32 v75, v9, v5
	v_or_b32_e32 v77, v12, v5
	v_bitop3_b32 v5, v4, v8, 4 bitop3:0x36
	v_bitop3_b32 v4, v4, v8, 6 bitop3:0x36
	v_lshl_add_u64 v[116:117], s[8:9], 0, v[2:3]
	v_lshl_add_u64 v[2:3], s[10:11], 0, v[34:35]
	v_lshlrev_b32_e32 v5, 4, v5
	v_lshlrev_b32_e32 v4, 4, v4
	v_lshl_add_u64 v[118:119], v[2:3], 0, v[32:33]
	v_mov_b32_e32 v2, 0
	v_or_b32_e32 v79, v9, v5
	v_or_b32_e32 v81, v12, v5
	v_or_b32_e32 v83, v9, v4
	v_or_b32_e32 v85, v12, v4
	s_mov_b32 s23, 0
	v_bitop3_b32 v104, v104, v41, v40 bitop3:0xf6
	v_or_b32_e32 v108, v108, v14
	v_bitop3_b32 v112, v112, v41, v40 bitop3:0xf6
	v_or_b32_e32 v116, v116, v32
	v_mov_b32_e32 v3, v2
	v_mov_b32_e32 v4, v2
	v_mov_b32_e32 v5, v2
	v_mov_b32_e32 v6, v2
	v_mov_b32_e32 v7, v2
	v_mov_b32_e32 v8, v2
	v_mov_b32_e32 v9, v2
	v_mov_b32_e32 v10, v2
	v_mov_b32_e32 v11, v2
	v_mov_b32_e32 v12, v2
	v_mov_b32_e32 v13, v2
	v_mov_b32_e32 v14, v2
	v_mov_b32_e32 v15, v2
	v_mov_b32_e32 v16, v2
	v_mov_b32_e32 v17, v2
	v_mov_b32_e32 v18, v2
	v_mov_b32_e32 v19, v2
	v_mov_b32_e32 v20, v2
	v_mov_b32_e32 v21, v2
	v_mov_b32_e32 v22, v2
	v_mov_b32_e32 v23, v2
	v_mov_b32_e32 v24, v2
	v_mov_b32_e32 v25, v2
	v_mov_b32_e32 v26, v2
	v_mov_b32_e32 v27, v2
	v_mov_b32_e32 v28, v2
	v_mov_b32_e32 v29, v2
	v_mov_b32_e32 v30, v2
	v_mov_b32_e32 v31, v2
	v_mov_b32_e32 v32, v2
	v_mov_b32_e32 v33, v2
	v_mov_b32_e32 v34, v2
	v_mov_b32_e32 v35, v2
	v_mov_b32_e32 v36, v2
	v_mov_b32_e32 v37, v2
	v_mov_b32_e32 v38, v2
	v_mov_b32_e32 v39, v2
	v_mov_b32_e32 v40, v2
	v_mov_b32_e32 v41, v2
	v_mov_b32_e32 v42, v2
	v_mov_b32_e32 v43, v2
	v_mov_b32_e32 v44, v2
	v_mov_b32_e32 v45, v2
	v_mov_b32_e32 v46, v2
	v_mov_b32_e32 v47, v2
	v_mov_b32_e32 v48, v2
	v_mov_b32_e32 v49, v2
	v_mov_b32_e32 v50, v2
	v_mov_b32_e32 v51, v2
	v_mov_b32_e32 v52, v2
	v_mov_b32_e32 v53, v2
	v_mov_b32_e32 v54, v2
	v_mov_b32_e32 v55, v2
	v_mov_b32_e32 v56, v2
	v_mov_b32_e32 v57, v2
	v_mov_b32_e32 v58, v2
	v_mov_b32_e32 v59, v2
	v_mov_b32_e32 v60, v2
	v_mov_b32_e32 v61, v2
	v_mov_b32_e32 v62, v2
	v_mov_b32_e32 v63, v2
	v_mov_b32_e32 v64, v2
	v_mov_b32_e32 v65, v2
	s_waitcnt vmcnt(0) lgkmcnt(0)
	s_barrier
	v_lshl_add_u64 v[104:105], s[80:81], 0, v[104:105]
	v_lshl_add_u64 v[104:105], v[104:105], 0, s[88:89]
	v_lshl_add_u64 v[106:107], s[80:81], 0, v[106:107]
	v_lshl_add_u64 v[106:107], v[106:107], 0, s[90:91]
	v_lshl_add_u64 v[108:109], s[80:81], 0, v[108:109]
	v_lshl_add_u64 v[108:109], v[108:109], 0, s[88:89]
	v_lshl_add_u64 v[110:111], s[80:81], 0, v[110:111]
	v_lshl_add_u64 v[110:111], v[110:111], 0, s[90:91]
	v_lshl_add_u64 v[112:113], s[80:81], 0, v[112:113]
	v_lshl_add_u64 v[112:113], v[112:113], 0, s[88:89]
	v_lshl_add_u64 v[114:115], s[80:81], 0, v[114:115]
	v_lshl_add_u64 v[114:115], v[114:115], 0, s[90:91]
	v_lshl_add_u64 v[116:117], s[80:81], 0, v[116:117]
	v_lshl_add_u64 v[116:117], v[116:117], 0, s[88:89]
	v_lshl_add_u64 v[118:119], s[80:81], 0, v[118:119]
	v_lshl_add_u64 v[118:119], v[118:119], 0, s[90:91]
	s_add_i32 m0, s5, 0x8000
	s_nop 0
	global_load_lds_dwordx4 v[104:105], off
	v_lshl_add_u64 v[104:105], v[104:105], 0, s[34:35]
	s_add_i32 m0, s5, 0xc000
	s_nop 0
	global_load_lds_dwordx4 v[106:107], off
	v_lshl_add_u64 v[106:107], v[106:107], 0, s[34:35]
	s_add_i32 m0, s5, 0x8400
	s_nop 0
	global_load_lds_dwordx4 v[108:109], off
	v_lshl_add_u64 v[108:109], v[108:109], 0, s[34:35]
	s_add_i32 m0, s5, 0xc400
	s_nop 0
	global_load_lds_dwordx4 v[110:111], off
	v_lshl_add_u64 v[110:111], v[110:111], 0, s[34:35]
	s_add_i32 m0, s5, 0x8800
	s_nop 0
	global_load_lds_dwordx4 v[112:113], off
	v_lshl_add_u64 v[112:113], v[112:113], 0, s[34:35]
	s_add_i32 m0, s5, 0xc800
	s_nop 0
	global_load_lds_dwordx4 v[114:115], off
	v_lshl_add_u64 v[114:115], v[114:115], 0, s[34:35]
	s_add_i32 m0, s5, 0x8c00
	s_nop 0
	global_load_lds_dwordx4 v[116:117], off
	v_lshl_add_u64 v[116:117], v[116:117], 0, s[34:35]
	s_add_i32 m0, s5, 0xcc00
	s_nop 0
	global_load_lds_dwordx4 v[118:119], off
	v_lshl_add_u64 v[118:119], v[118:119], 0, s[34:35]
	s_mov_b32 s23, 0
.Lg1o_loop:
	ds_read_b128 v[128:131], v71 offset:0
	ds_read_b128 v[136:139], v73 offset:0
	ds_read_b128 v[132:135], v71 offset:4096
	ds_read_b128 v[140:143], v73 offset:4096
	ds_read_b128 v[184:187], v75 offset:0
	ds_read_b128 v[192:195], v77 offset:0
	ds_read_b128 v[188:191], v75 offset:4096
	ds_read_b128 v[196:199], v77 offset:4096
	ds_read_b128 v[200:203], v79 offset:0
	ds_read_b128 v[208:211], v81 offset:0
	ds_read_b128 v[204:207], v79 offset:4096
	ds_read_b128 v[212:215], v81 offset:4096
	ds_read_b128 v[216:219], v83 offset:0
	ds_read_b128 v[224:227], v85 offset:0
	ds_read_b128 v[220:223], v83 offset:4096
	ds_read_b128 v[228:231], v85 offset:4096
	s_waitcnt lgkmcnt(12)
	v_mfma_f32_32x32x16_bf16 v[50:65], v[128:131], v[136:139], v[50:65]
	v_mfma_f32_32x32x16_bf16 v[34:49], v[128:131], v[140:143], v[34:49]
	v_mfma_f32_32x32x16_bf16 v[18:33], v[132:135], v[136:139], v[18:33]
	v_mfma_f32_32x32x16_bf16 v[2:17], v[132:135], v[140:143], v[2:17]
	s_waitcnt lgkmcnt(8)
	v_mfma_f32_32x32x16_bf16 v[50:65], v[184:187], v[192:195], v[50:65]
	v_mfma_f32_32x32x16_bf16 v[34:49], v[184:187], v[196:199], v[34:49]
	v_mfma_f32_32x32x16_bf16 v[18:33], v[188:191], v[192:195], v[18:33]
	v_mfma_f32_32x32x16_bf16 v[2:17], v[188:191], v[196:199], v[2:17]
	s_waitcnt lgkmcnt(0)
	s_barrier
	s_mov_b32 m0, s5
	v_mfma_f32_32x32x16_bf16 v[50:65], v[200:203], v[208:211], v[50:65]
	global_load_lds_dwordx4 v[104:105], off
	v_lshl_add_u64 v[104:105], v[104:105], 0, s[34:35]
	s_mov_b32 m0, s15
	v_mfma_f32_32x32x16_bf16 v[34:49], v[200:203], v[212:215], v[34:49]
	global_load_lds_dwordx4 v[106:107], off
	v_lshl_add_u64 v[106:107], v[106:107], 0, s[34:35]
	s_add_i32 m0, s5, 0x400
	v_mfma_f32_32x32x16_bf16 v[18:33], v[204:207], v[208:211], v[18:33]
	global_load_lds_dwordx4 v[108:109], off
	v_lshl_add_u64 v[108:109], v[108:109], 0, s[34:35]
	s_mov_b32 m0, s16
	v_mfma_f32_32x32x16_bf16 v[2:17], v[204:207], v[212:215], v[2:17]
	global_load_lds_dwordx4 v[110:111], off
	v_lshl_add_u64 v[110:111], v[110:111], 0, s[34:35]
	s_add_i32 m0, s5, 0x800
	v_mfma_f32_32x32x16_bf16 v[50:65], v[216:219], v[224:227], v[50:65]
	global_load_lds_dwordx4 v[112:113], off
	v_lshl_add_u64 v[112:113], v[112:113], 0, s[34:35]
	s_mov_b32 m0, s17
	v_mfma_f32_32x32x16_bf16 v[34:49], v[216:219], v[228:231], v[34:49]
	global_load_lds_dwordx4 v[114:115], off
	v_lshl_add_u64 v[114:115], v[114:115], 0, s[34:35]
	s_add_i32 m0, s5, 0xc00
	v_mfma_f32_32x32x16_bf16 v[18:33], v[220:223], v[224:227], v[18:33]
	global_load_lds_dwordx4 v[116:117], off
	v_lshl_add_u64 v[116:117], v[116:117], 0, s[34:35]
	s_mov_b32 m0, s22
	v_mfma_f32_32x32x16_bf16 v[2:17], v[220:223], v[228:231], v[2:17]
	global_load_lds_dwordx4 v[118:119], off
	v_lshl_add_u64 v[118:119], v[118:119], 0, s[34:35]
	s_waitcnt vmcnt(8)
	s_barrier
	ds_read_b128 v[128:131], v71 offset:32768
	ds_read_b128 v[136:139], v73 offset:32768
	ds_read_b128 v[132:135], v71 offset:36864
	ds_read_b128 v[140:143], v73 offset:36864
	ds_read_b128 v[184:187], v75 offset:32768
	ds_read_b128 v[192:195], v77 offset:32768
	ds_read_b128 v[188:191], v75 offset:36864
	ds_read_b128 v[196:199], v77 offset:36864
	ds_read_b128 v[200:203], v79 offset:32768
	ds_read_b128 v[208:211], v81 offset:32768
	ds_read_b128 v[204:207], v79 offset:36864
	ds_read_b128 v[212:215], v81 offset:36864
	ds_read_b128 v[216:219], v83 offset:32768
	ds_read_b128 v[224:227], v85 offset:32768
	ds_read_b128 v[220:223], v83 offset:36864
	ds_read_b128 v[228:231], v85 offset:36864
	s_waitcnt lgkmcnt(12)
	v_mfma_f32_32x32x16_bf16 v[50:65], v[128:131], v[136:139], v[50:65]
	v_mfma_f32_32x32x16_bf16 v[34:49], v[128:131], v[140:143], v[34:49]
	v_mfma_f32_32x32x16_bf16 v[18:33], v[132:135], v[136:139], v[18:33]
	v_mfma_f32_32x32x16_bf16 v[2:17], v[132:135], v[140:143], v[2:17]
	s_waitcnt lgkmcnt(8)
	v_mfma_f32_32x32x16_bf16 v[50:65], v[184:187], v[192:195], v[50:65]
	v_mfma_f32_32x32x16_bf16 v[34:49], v[184:187], v[196:199], v[34:49]
	v_mfma_f32_32x32x16_bf16 v[18:33], v[188:191], v[192:195], v[18:33]
	v_mfma_f32_32x32x16_bf16 v[2:17], v[188:191], v[196:199], v[2:17]
	s_waitcnt lgkmcnt(0)
	s_barrier
	s_add_i32 m0, s5, 0x8000
	v_mfma_f32_32x32x16_bf16 v[50:65], v[200:203], v[208:211], v[50:65]
	global_load_lds_dwordx4 v[104:105], off
	v_lshl_add_u64 v[104:105], v[104:105], 0, s[34:35]
	s_add_i32 m0, s5, 0xc000
	v_mfma_f32_32x32x16_bf16 v[34:49], v[200:203], v[212:215], v[34:49]
	global_load_lds_dwordx4 v[106:107], off
	v_lshl_add_u64 v[106:107], v[106:107], 0, s[34:35]
	s_add_i32 m0, s5, 0x8400
	v_mfma_f32_32x32x16_bf16 v[18:33], v[204:207], v[208:211], v[18:33]
	global_load_lds_dwordx4 v[108:109], off
	v_lshl_add_u64 v[108:109], v[108:109], 0, s[34:35]
	s_add_i32 m0, s5, 0xc400
	v_mfma_f32_32x32x16_bf16 v[2:17], v[204:207], v[212:215], v[2:17]
	global_load_lds_dwordx4 v[110:111], off
	v_lshl_add_u64 v[110:111], v[110:111], 0, s[34:35]
	s_add_i32 m0, s5, 0x8800
	v_mfma_f32_32x32x16_bf16 v[50:65], v[216:219], v[224:227], v[50:65]
	global_load_lds_dwordx4 v[112:113], off
	v_lshl_add_u64 v[112:113], v[112:113], 0, s[34:35]
	s_add_i32 m0, s5, 0xc800
	v_mfma_f32_32x32x16_bf16 v[34:49], v[216:219], v[228:231], v[34:49]
	global_load_lds_dwordx4 v[114:115], off
	v_lshl_add_u64 v[114:115], v[114:115], 0, s[34:35]
	s_add_i32 m0, s5, 0x8c00
	v_mfma_f32_32x32x16_bf16 v[18:33], v[220:223], v[224:227], v[18:33]
	global_load_lds_dwordx4 v[116:117], off
	v_lshl_add_u64 v[116:117], v[116:117], 0, s[34:35]
	s_add_i32 m0, s5, 0xcc00
	v_mfma_f32_32x32x16_bf16 v[2:17], v[220:223], v[228:231], v[2:17]
	global_load_lds_dwordx4 v[118:119], off
	v_lshl_add_u64 v[118:119], v[118:119], 0, s[34:35]
	s_waitcnt vmcnt(8)
	s_barrier
	s_add_i32 s23, s23, 2
	s_cmp_lt_u32 s23, 14
	s_cbranch_scc1 .Lg1o_loop
	ds_read_b128 v[128:131], v71 offset:0
	ds_read_b128 v[136:139], v73 offset:0
	ds_read_b128 v[132:135], v71 offset:4096
	ds_read_b128 v[140:143], v73 offset:4096
	ds_read_b128 v[184:187], v75 offset:0
	ds_read_b128 v[192:195], v77 offset:0
	ds_read_b128 v[188:191], v75 offset:4096
	ds_read_b128 v[196:199], v77 offset:4096
	ds_read_b128 v[200:203], v79 offset:0
	ds_read_b128 v[208:211], v81 offset:0
	ds_read_b128 v[204:207], v79 offset:4096
	ds_read_b128 v[212:215], v81 offset:4096
	ds_read_b128 v[216:219], v83 offset:0
	ds_read_b128 v[224:227], v85 offset:0
	ds_read_b128 v[220:223], v83 offset:4096
	ds_read_b128 v[228:231], v85 offset:4096
	s_waitcnt lgkmcnt(12)
	v_mfma_f32_32x32x16_bf16 v[50:65], v[128:131], v[136:139], v[50:65]
	v_mfma_f32_32x32x16_bf16 v[34:49], v[128:131], v[140:143], v[34:49]
	v_mfma_f32_32x32x16_bf16 v[18:33], v[132:135], v[136:139], v[18:33]
	v_mfma_f32_32x32x16_bf16 v[2:17], v[132:135], v[140:143], v[2:17]
	s_waitcnt lgkmcnt(8)
	v_mfma_f32_32x32x16_bf16 v[50:65], v[184:187], v[192:195], v[50:65]
	v_mfma_f32_32x32x16_bf16 v[34:49], v[184:187], v[196:199], v[34:49]
	v_mfma_f32_32x32x16_bf16 v[18:33], v[188:191], v[192:195], v[18:33]
	v_mfma_f32_32x32x16_bf16 v[2:17], v[188:191], v[196:199], v[2:17]
	s_waitcnt lgkmcnt(0)
	s_barrier
	v_mfma_f32_32x32x16_bf16 v[50:65], v[200:203], v[208:211], v[50:65]
	v_mfma_f32_32x32x16_bf16 v[34:49], v[200:203], v[212:215], v[34:49]
	v_mfma_f32_32x32x16_bf16 v[18:33], v[204:207], v[208:211], v[18:33]
	v_mfma_f32_32x32x16_bf16 v[2:17], v[204:207], v[212:215], v[2:17]
	v_mfma_f32_32x32x16_bf16 v[50:65], v[216:219], v[224:227], v[50:65]
	v_mfma_f32_32x32x16_bf16 v[34:49], v[216:219], v[228:231], v[34:49]
	v_mfma_f32_32x32x16_bf16 v[18:33], v[220:223], v[224:227], v[18:33]
	v_mfma_f32_32x32x16_bf16 v[2:17], v[220:223], v[228:231], v[2:17]
	s_waitcnt vmcnt(0)
	s_barrier
	ds_read_b128 v[128:131], v71 offset:32768
	ds_read_b128 v[136:139], v73 offset:32768
	ds_read_b128 v[132:135], v71 offset:36864
	ds_read_b128 v[140:143], v73 offset:36864
	ds_read_b128 v[184:187], v75 offset:32768
	ds_read_b128 v[192:195], v77 offset:32768
	ds_read_b128 v[188:191], v75 offset:36864
	ds_read_b128 v[196:199], v77 offset:36864
	ds_read_b128 v[200:203], v79 offset:32768
	ds_read_b128 v[208:211], v81 offset:32768
	ds_read_b128 v[204:207], v79 offset:36864
	ds_read_b128 v[212:215], v81 offset:36864
	ds_read_b128 v[216:219], v83 offset:32768
	ds_read_b128 v[224:227], v85 offset:32768
	ds_read_b128 v[220:223], v83 offset:36864
	ds_read_b128 v[228:231], v85 offset:36864
	s_waitcnt lgkmcnt(12)
	v_mfma_f32_32x32x16_bf16 v[50:65], v[128:131], v[136:139], v[50:65]
	v_mfma_f32_32x32x16_bf16 v[34:49], v[128:131], v[140:143], v[34:49]
	v_mfma_f32_32x32x16_bf16 v[18:33], v[132:135], v[136:139], v[18:33]
	v_mfma_f32_32x32x16_bf16 v[2:17], v[132:135], v[140:143], v[2:17]
	s_waitcnt lgkmcnt(8)
	v_mfma_f32_32x32x16_bf16 v[50:65], v[184:187], v[192:195], v[50:65]
	v_mfma_f32_32x32x16_bf16 v[34:49], v[184:187], v[196:199], v[34:49]
	v_mfma_f32_32x32x16_bf16 v[18:33], v[188:191], v[192:195], v[18:33]
	v_mfma_f32_32x32x16_bf16 v[2:17], v[188:191], v[196:199], v[2:17]
	s_waitcnt lgkmcnt(0)
	s_barrier
	v_mfma_f32_32x32x16_bf16 v[50:65], v[200:203], v[208:211], v[50:65]
	v_mfma_f32_32x32x16_bf16 v[34:49], v[200:203], v[212:215], v[34:49]
	v_mfma_f32_32x32x16_bf16 v[18:33], v[204:207], v[208:211], v[18:33]
	v_mfma_f32_32x32x16_bf16 v[2:17], v[204:207], v[212:215], v[2:17]
	v_mfma_f32_32x32x16_bf16 v[50:65], v[216:219], v[224:227], v[50:65]
	v_mfma_f32_32x32x16_bf16 v[34:49], v[216:219], v[228:231], v[34:49]
	v_mfma_f32_32x32x16_bf16 v[18:33], v[220:223], v[224:227], v[18:33]
	v_mfma_f32_32x32x16_bf16 v[2:17], v[220:223], v[228:231], v[2:17]
	s_waitcnt vmcnt(0) lgkmcnt(0)
	s_barrier
	s_branch .LBB0_993
